# phase-3 weight conversion: process pairs of consecutive k-tiles per iteration (2x loads in flight)
# speedup vs baseline: 1.0121x; 1.0121x over previous
.LBB0_208:
	s_abs_i32 s0, s68
	v_cvt_f32_u32_e32 v0, s0
	s_sub_i32 s1, 0, s0
	v_writelane_b32 v254, s96, 8
	v_rcp_iflag_f32_e32 v0, v0
	s_nop 0
	v_writelane_b32 v254, s97, 9
	v_mul_f32_e32 v0, 0x4f7ffffe, v0
	v_cvt_u32_f32_e32 v0, v0
	s_nop 0
	v_readfirstlane_b32 s4, v0
	s_mul_i32 s1, s1, s4
	s_mul_hi_u32 s1, s4, s1
	s_add_i32 s4, s4, s1
	s_mul_hi_u32 s1, s4, 0x280
	s_mul_i32 s1, s1, s0
	s_sub_i32 s1, 0x280, s1
	s_sub_i32 s4, s1, s0
	s_cmp_ge_u32 s1, s0
	s_cselect_b32 s1, s4, s1
	s_sub_i32 s4, s1, s0
	s_cmp_ge_u32 s1, s0
	s_cselect_b32 s0, s4, s1
	s_sub_i32 s97, s2, s0
	s_sub_i32 s64, s68, s0
	s_lshl_b32 s84, s97, 1
	s_lshl_b32 s85, s64, 1
	s_cmp_lt_i32 s97, 0
	v_writelane_b32 v254, s0, 10
	s_cbranch_scc1 .LBB0_267
	s_cmpk_gt_u32 s84, 0xebf
	s_waitcnt vmcnt(0) lgkmcnt(0)
	s_barrier
	s_cbranch_scc1 .LBB0_267
	s_cmpk_lt_u32 s84, 0x580
	s_movk_i32 s0, 0x840
	s_cselect_b32 s1, 0x580, s0
	s_add_i32 s1, s1, s84
	s_cmpk_gt_u32 s1, 0xaff
	s_cbranch_scc0 .LBB0_217
	s_cmpk_gt_u32 s1, 0x107f
	s_cbranch_scc0 .LBB0_218
	s_cmpk_gt_u32 s1, 0x12ff
	s_cbranch_scc0 .LBB0_219
	s_cmpk_gt_u32 s1, 0x14ff
	s_cbranch_scc0 .LBB0_220
	s_cmpk_gt_u32 s1, 0x157f
	s_cbranch_scc0 .LBB0_221
	s_lshl_b32 s7, s1, 6
	s_cmpk_gt_u32 s1, 0x15ff
	s_cbranch_scc0 .LBB0_222
	s_lshl_b32 s0, s1, 2
	s_and_b32 s0, s0, 0x7fc0
	s_add_i32 s6, s0, 0xffffa800
	s_and_b32 s0, s7, 0x3c0
	s_mov_b64 s[8:9], 0
	s_mov_b64 s[4:5], s[50:51]
	s_branch .LBB0_223

.LBB0_238:
	s_add_i32 s0, s1, 0xfffffa80
	s_lshl_b32 s4, s0, 2
	s_bfe_i32 s5, s84, 0x10005
	s_lshl_b32 s0, s0, 1
	s_and_b32 s5, s5, 0xb00
	s_and_b32 s0, s0, 0x7fffff80
	s_and_b32 s20, s4, 0x7fffffc0
	s_add_i32 s0, s0, s5
	s_and_b32 s4, s4, 64
	s_or_b32 s6, s0, s4
	s_lshl_b32 s0, s1, 6
	s_and_b32 s0, s0, 0x3c0
	s_add_u32 s4, s38, 0x1600000
	s_addc_u32 s5, s39, 0
	s_movk_i32 s24, 0x400
	s_mov_b64 s[16:17], 0x1600
	s_mov_b64 s[8:9], 0xb00000
.LBB0_239:
	s_ashr_i32 s1, s0, 31
	s_mul_hi_u32 s7, s16, s0
	s_mul_i32 s18, s16, s1
	s_add_i32 s7, s7, s18
	s_mul_i32 s17, s17, s0
	s_add_i32 s19, s7, s17
	s_mul_i32 s18, s16, s0
	s_lshl_b64 s[18:19], s[18:19], 2
	s_add_u32 s17, s4, s18
	s_addc_u32 s18, s5, s19
	s_ashr_i32 s7, s6, 31
	s_lshl_b64 s[4:5], s[6:7], 2
	s_add_u32 s4, s17, s4
	v_add_u32_e32 v14, 32, v194
	v_mov_b32_e32 v9, 0
	v_mul_u32_u24_e32 v2, s16, v194
	s_addc_u32 s5, s18, s5
	v_mul_hi_u32_u24_e32 v1, s16, v14
	v_mul_u32_u24_e32 v0, s16, v14
	v_lshlrev_b32_e32 v2, 2, v2
	v_mov_b32_e32 v3, v9
	v_lshl_add_u64 v[0:1], v[0:1], 2, s[4:5]
	v_lshlrev_b32_e32 v8, 4, v181
	v_lshl_add_u64 v[2:3], s[4:5], 0, v[2:3]
	v_lshl_add_u64 v[0:1], v[0:1], 0, v[8:9]
	v_lshl_add_u64 v[2:3], v[2:3], 0, v[8:9]
	s_lshl_b32 s86, s16, 8
	s_mov_b32 s87, 0
	v_lshl_add_u64 v[28:29], v[0:1], 0, s[86:87]
	v_lshl_add_u64 v[30:31], v[2:3], 0, s[86:87]
	global_load_dwordx4 v[4:7], v[0:1], off
	s_nop 0
	global_load_dwordx4 v[0:3], v[2:3], off
	global_load_dwordx4 v[36:39], v[28:29], off
	global_load_dwordx4 v[32:35], v[30:31], off
	s_add_u32 s6, s34, s8
	s_addc_u32 s7, s35, s9
	s_ashr_i32 s4, s20, 31
	s_mul_hi_u32 s5, s24, s20
	s_mul_i32 s4, s24, s4
	s_add_i32 s5, s5, s4
	s_mul_i32 s4, s24, s20
	s_lshl_b64 s[4:5], s[4:5], 1
	s_add_u32 s4, s6, s4
	s_addc_u32 s5, s7, s5
	s_lshl_b64 s[0:1], s[0:1], 1
	v_mul_u32_u24_e32 v11, 0x104, v194
	s_add_u32 s4, s4, s0
	v_add3_u32 v15, 0, v11, v8
	v_lshlrev_b32_e32 v8, 3, v146
	v_readlane_b32 s7, v254, 10
	s_addc_u32 s5, s5, s1
	v_and_b32_e32 v8, 56, v8
	s_lshl_b32 s0, s7, 1
	s_add_i32 s6, s2, s68
	v_mul_u32_u24_e32 v11, 0x104, v8
	v_lshlrev_b32_e32 v12, 2, v128
	s_sub_i32 s25, s68, s0
	s_sub_i32 s0, s6, s0
	v_lshlrev_b32_e32 v10, 2, v181
	v_add3_u32 v16, 0, v11, v12
	s_lshl_b32 s26, s0, 6
	s_lshl_b32 s0, s68, 6
	s_lshl_b32 s6, s7, 6
	s_mov_b32 s1, 0
	s_sub_i32 s27, s0, s6
	s_sub_i32 s33, 0, s7
	v_add_u32_e32 v17, 0x2080, v15
	v_add_u32_e32 v18, 0x2088, v15
	v_add_u32_e32 v40, 0x4100, v15
	v_add_u32_e32 v41, 0x6180, v15
	v_add_u32_e32 v42, 0x6188, v15
	s_movk_i32 s65, 0x840
	s_mov_b32 s70, 0x1600000
	v_lshlrev_b32_e32 v10, 2, v10
	v_lshlrev_b32_e32 v12, 1, v8
	v_add_u32_e32 v19, 0x400, v16
	v_add_u32_e32 v43, 0x4100, v16
	v_add_u32_e32 v44, 0x4500, v16
	v_mov_b32_e32 v13, v9
	s_mov_b32 s71, s2
	s_lshl_b32 s25, s25, 1
	s_lshl_b32 s26, s26, 1
	s_lshl_b32 s27, s27, 1
	s_lshl_b32 s33, s33, 1
	s_lshl_b32 s71, s71, 1
	s_branch .LBB0_242
.LBB0_240:
	s_add_u32 s0, s34, s20
	s_addc_u32 s22, s35, s21
	s_ashr_i32 s7, s6, 31
	s_mul_hi_u32 s17, s18, s6
	s_mul_i32 s20, s18, s7
	s_add_i32 s17, s17, s20
	s_mul_i32 s19, s19, s6
	s_add_i32 s21, s17, s19
	s_mul_i32 s20, s18, s6
	s_ashr_i32 s17, s16, 31
	s_lshl_b64 s[20:21], s[20:21], 2
	s_add_u32 s19, s8, s20
	s_addc_u32 s20, s9, s21
	s_lshl_b64 s[8:9], s[16:17], 2
	s_add_u32 s8, s19, s8
	v_mul_u32_u24_e32 v0, s18, v194
	s_addc_u32 s9, s20, s9
	v_lshlrev_b32_e32 v8, 2, v0
	v_mul_hi_u32_u24_e32 v3, s18, v14
	v_mul_u32_u24_e32 v2, s18, v14
	v_lshl_add_u64 v[0:1], s[8:9], 0, v[8:9]
	v_mov_b32_e32 v11, v9
	v_lshl_add_u64 v[2:3], v[2:3], 2, s[8:9]
	v_lshl_add_u64 v[0:1], v[0:1], 0, v[10:11]
	v_lshl_add_u64 v[4:5], v[2:3], 0, v[10:11]
	s_lshl_b32 s86, s18, 8
	s_mov_b32 s87, 0
	v_lshl_add_u64 v[28:29], v[0:1], 0, s[86:87]
	v_lshl_add_u64 v[30:31], v[4:5], 0, s[86:87]
	global_load_dwordx4 v[0:3], v[0:1], off
	s_nop 0
	global_load_dwordx4 v[4:7], v[4:5], off
	global_load_dwordx4 v[32:35], v[28:29], off
	global_load_dwordx4 v[36:39], v[30:31], off
	s_ashr_i32 s8, s74, 31
	s_mul_hi_u32 s9, s72, s74
	s_mul_i32 s8, s72, s8
	s_add_i32 s9, s9, s8
	s_mul_i32 s8, s72, s74
	s_lshl_b64 s[8:9], s[8:9], 1
	s_add_u32 s0, s0, s8
	s_addc_u32 s8, s22, s9
	s_lshl_b64 s[6:7], s[6:7], 1
	s_add_u32 s6, s0, s6
	s_addc_u32 s7, s8, s7
.LBB0_241:
	s_waitcnt lgkmcnt(0)
	s_barrier
	ds_read2_b32 v[20:21], v16 offset1:65
	ds_read2_b32 v[22:23], v16 offset0:130 offset1:195
	ds_read2_b32 v[24:25], v19 offset0:4 offset1:69
	ds_read2_b32 v[26:27], v19 offset0:134 offset1:199
	ds_read2_b32 v[48:49], v43 offset1:65
	ds_read2_b32 v[50:51], v43 offset0:130 offset1:195
	ds_read2_b32 v[52:53], v44 offset0:4 offset1:69
	ds_read2_b32 v[54:55], v44 offset0:134 offset1:199
	s_add_i32 s71, s71, s85
	s_waitcnt lgkmcnt(7)
	v_cvt_pk_bf16_f32 v20, v20, v21
	s_waitcnt lgkmcnt(6)
	v_cvt_pk_bf16_f32 v21, v22, v23
	s_waitcnt lgkmcnt(5)
	v_cvt_pk_bf16_f32 v22, v24, v25
	v_mad_u64_u32 v[24:25], s[8:9], s24, v128, 0
	v_lshl_add_u64 v[24:25], v[24:25], 1, s[4:5]
	s_waitcnt lgkmcnt(4)
	v_cvt_pk_bf16_f32 v23, v26, v27
	v_lshl_add_u64 v[24:25], v[24:25], 0, v[12:13]
	global_store_dwordx4 v[24:25], v[20:23], off
	s_waitcnt lgkmcnt(3)
	v_cvt_pk_bf16_f32 v56, v48, v49
	s_waitcnt lgkmcnt(2)
	v_cvt_pk_bf16_f32 v57, v50, v51
	s_waitcnt lgkmcnt(1)
	v_cvt_pk_bf16_f32 v58, v52, v53
	s_waitcnt lgkmcnt(0)
	v_cvt_pk_bf16_f32 v59, v54, v55
	global_store_dwordx4 v[24:25], v[56:59], off offset:128
	s_waitcnt lgkmcnt(0)
	s_barrier
	s_add_i32 s26, s26, s27
	s_add_i32 s0, s33, s71
	s_cmpk_lt_i32 s0, 0xec0
	s_mov_b64 s[4:5], s[6:7]
	s_mov_b32 s24, s72
	s_cbranch_scc0 .LBB0_267
.LBB0_242:
	s_add_i32 s17, s25, s71
	s_mov_b64 s[6:7], 0
	s_cmpk_gt_i32 s17, 0xebf
	s_mov_b32 s72, 0
	s_waitcnt vmcnt(0)
	ds_write2_b32 v15, v0, v1 offset1:1
	ds_write2_b32 v17, v4, v5 offset1:1
	ds_write2_b32 v15, v2, v3 offset0:2 offset1:3
	ds_write2_b32 v18, v6, v7 offset1:1
	ds_write2_b32 v40, v32, v33 offset1:1
	ds_write2_b32 v41, v36, v37 offset1:1
	ds_write2_b32 v40, v34, v35 offset0:2 offset1:3
	ds_write2_b32 v42, v38, v39 offset1:1
	s_cbranch_scc1 .LBB0_241
	s_cmpk_lt_i32 s17, 0x580
	s_cselect_b32 s73, 0x580, s65
	s_add_i32 s7, s25, s73
	s_add_i32 s7, s7, s71
	s_cmpk_gt_i32 s7, 0xaff
	s_mov_b64 s[22:23], -1
	s_cbranch_scc0 .LBB0_263
	s_cmpk_gt_u32 s7, 0x107f
	s_cbranch_scc0 .LBB0_260
	s_cmpk_gt_u32 s7, 0x12ff
	s_cbranch_scc0 .LBB0_251
	s_cmpk_gt_u32 s7, 0x14ff
	s_cbranch_scc0 .LBB0_252
	s_cmpk_gt_u32 s7, 0x157f
	s_cbranch_scc0 .LBB0_253
	s_lshl_b32 s0, s7, 6
	s_cmpk_gt_u32 s7, 0x15ff
	s_cbranch_scc0 .LBB0_265
	s_lshl_b32 s6, s7, 2
	s_and_b32 s6, s6, 0x7fffffc0
	s_add_i32 s16, s6, 0xffffa800
	s_and_b32 s6, s0, 0x3c0
	s_mov_b64 s[8:9], s[50:51]
	s_cbranch_execz .LBB0_266
	s_mov_b64 s[20:21], 0x2f00000
	s_movk_i32 s72, 0x400
	s_cbranch_execz .LBB0_254
	s_branch .LBB0_255
